# prep_gdn K K^T / Q K^T tiles hand-scheduled: A/B fragments read once in two batches (24 ds_read_b128 instead of 48) and the 32 MFMAs run back to back instead of behind one LDS round trip each
# speedup vs baseline: 1.0131x; 1.0110x over previous
.LBB0_293:
	s_or_b64 exec, exec, s[0:1]
	v_and_b32_e32 v3, 48, v14
	v_and_b32_e32 v17, 15, v38
	v_lshrrev_b32_e32 v1, 1, v38
	v_add_u32_e32 v18, v2, v3
	v_lshrrev_b32_e32 v2, 2, v14
	v_and_b32_e32 v19, 12, v2
	v_lshlrev_b32_e32 v2, 2, v17
	v_and_b32_e32 v25, 32, v1
	v_add3_u32 v20, v196, v0, v2
	v_or_b32_e32 v0, v25, v17
	v_mad_u32_u24 v36, v0, s71, v18
	v_mul_u32_u24_e32 v0, 0x110, v17
	s_waitcnt lgkmcnt(0)
	s_barrier
	v_add3_u32 v38, v196, v3, v0
	ds_read_b128 v[208:211], v36
	ds_read_b128 v[212:215], v36 offset:64
	ds_read_b128 v[216:219], v36 offset:128
	ds_read_b128 v[220:223], v36 offset:192
	ds_read_b128 v[0:3], v38 offset:21504
	ds_read_b128 v[4:7], v38 offset:21568
	ds_read_b128 v[46:49], v38 offset:21632
	ds_read_b128 v[108:111], v38 offset:21696
	ds_read_b128 v[42:45], v38 offset:25856
	ds_read_b128 v[118:121], v38 offset:25920
	ds_read_b128 v[122:125], v38 offset:25984
	ds_read_b128 v[128:131], v38 offset:26048
	v_or_b32_e32 v39, v25, v19
	v_lshl_add_u32 v39, v39, 8, v20
	v_or_b32_e32 v25, 16, v25
	v_or_b32_e32 v248, v25, v17
	v_mad_u32_u24 v249, v248, s71, v18
	v_lshl_add_u32 v18, v194, 2, v196
	v_or_b32_e32 v248, v25, v19
	v_lshl_add_u32 v8, v248, 8, v20
	s_waitcnt lgkmcnt(0)
	ds_read_b128 v[112:115], v38 offset:30208
	ds_read_b128 v[144:147], v38 offset:30272
	ds_read_b128 v[148:151], v38 offset:30336
	ds_read_b128 v[152:155], v38 offset:30400
	ds_read_b128 v[132:135], v38 offset:34560
	ds_read_b128 v[160:163], v38 offset:34624
	ds_read_b128 v[166:169], v38 offset:34688
	ds_read_b128 v[170:173], v38 offset:34752
	ds_read_b128 v[224:227], v249
	ds_read_b128 v[228:231], v249 offset:64
	ds_read_b128 v[232:235], v249 offset:128
	ds_read_b128 v[236:239], v249 offset:192
	v_mfma_f32_16x16x32_bf16 v[244:247], v[208:211], v[0:3], 0
	v_mfma_f32_16x16x32_bf16 v[244:247], v[212:215], v[4:7], v[244:247]
	v_mfma_f32_16x16x32_bf16 v[244:247], v[216:219], v[46:49], v[244:247]
	v_mfma_f32_16x16x32_bf16 v[244:247], v[220:223], v[108:111], v[244:247]
	v_mfma_f32_16x16x32_bf16 v[240:243], v[208:211], v[42:45], 0
	v_mfma_f32_16x16x32_bf16 v[240:243], v[212:215], v[118:121], v[240:243]
	v_mfma_f32_16x16x32_bf16 v[240:243], v[216:219], v[122:125], v[240:243]
	v_mfma_f32_16x16x32_bf16 v[240:243], v[220:223], v[128:131], v[240:243]
	s_waitcnt lgkmcnt(0)
	s_nop 3
	ds_write_b32 v39, v244 offset:4096
	ds_write_b32 v39, v245 offset:4352
	ds_write_b32 v39, v246 offset:4608
	ds_write_b32 v39, v247 offset:4864
	v_mfma_f32_16x16x32_bf16 v[244:247], v[208:211], v[112:115], 0
	v_mfma_f32_16x16x32_bf16 v[244:247], v[212:215], v[144:147], v[244:247]
	v_mfma_f32_16x16x32_bf16 v[244:247], v[216:219], v[148:151], v[244:247]
	v_mfma_f32_16x16x32_bf16 v[244:247], v[220:223], v[152:155], v[244:247]
	s_nop 3
	ds_write_b32 v39, v240 offset:4160
	ds_write_b32 v39, v241 offset:4416
	ds_write_b32 v39, v242 offset:4672
	ds_write_b32 v39, v243 offset:4928
	v_mfma_f32_16x16x32_bf16 v[240:243], v[208:211], v[132:135], 0
	v_mfma_f32_16x16x32_bf16 v[240:243], v[212:215], v[160:163], v[240:243]
	v_mfma_f32_16x16x32_bf16 v[240:243], v[216:219], v[166:169], v[240:243]
	v_mfma_f32_16x16x32_bf16 v[240:243], v[220:223], v[170:173], v[240:243]
	s_nop 3
	ds_write_b32 v39, v244 offset:4224
	ds_write_b32 v39, v245 offset:4480
	ds_write_b32 v39, v246 offset:4736
	ds_write_b32 v39, v247 offset:4992
	s_waitcnt lgkmcnt(8)
	v_mfma_f32_16x16x32_bf16 v[244:247], v[224:227], v[0:3], 0
	v_mfma_f32_16x16x32_bf16 v[244:247], v[228:231], v[4:7], v[244:247]
	v_mfma_f32_16x16x32_bf16 v[244:247], v[232:235], v[46:49], v[244:247]
	v_mfma_f32_16x16x32_bf16 v[244:247], v[236:239], v[108:111], v[244:247]
	s_nop 3
	ds_write_b32 v39, v240 offset:4288
	ds_write_b32 v39, v241 offset:4544
	ds_write_b32 v39, v242 offset:4800
	ds_write_b32 v39, v243 offset:5056
	s_waitcnt lgkmcnt(8)
	v_mfma_f32_16x16x32_bf16 v[240:243], v[224:227], v[42:45], 0
	v_mfma_f32_16x16x32_bf16 v[240:243], v[228:231], v[118:121], v[240:243]
	v_mfma_f32_16x16x32_bf16 v[240:243], v[232:235], v[122:125], v[240:243]
	v_mfma_f32_16x16x32_bf16 v[240:243], v[236:239], v[128:131], v[240:243]
	s_nop 3
	ds_write_b32 v8, v244 offset:4096
	ds_write_b32 v8, v245 offset:4352
	ds_write_b32 v8, v246 offset:4608
	ds_write_b32 v8, v247 offset:4864
	s_waitcnt lgkmcnt(8)
	v_mfma_f32_16x16x32_bf16 v[244:247], v[224:227], v[112:115], 0
	v_mfma_f32_16x16x32_bf16 v[244:247], v[228:231], v[144:147], v[244:247]
	v_mfma_f32_16x16x32_bf16 v[244:247], v[232:235], v[148:151], v[244:247]
	v_mfma_f32_16x16x32_bf16 v[244:247], v[236:239], v[152:155], v[244:247]
	s_nop 3
	ds_write_b32 v8, v240 offset:4160
	ds_write_b32 v8, v241 offset:4416
	ds_write_b32 v8, v242 offset:4672
	ds_write_b32 v8, v243 offset:4928
	s_waitcnt lgkmcnt(8)
	v_mfma_f32_16x16x32_bf16 v[240:243], v[224:227], v[132:135], 0
	v_mfma_f32_16x16x32_bf16 v[240:243], v[228:231], v[160:163], v[240:243]
	v_mfma_f32_16x16x32_bf16 v[240:243], v[232:235], v[166:169], v[240:243]
	v_mfma_f32_16x16x32_bf16 v[240:243], v[236:239], v[170:173], v[240:243]
	s_nop 3
	ds_write_b32 v8, v244 offset:4224
	ds_write_b32 v8, v245 offset:4480
	ds_write_b32 v8, v246 offset:4736
	ds_write_b32 v8, v247 offset:4992
	s_waitcnt lgkmcnt(8)
	s_nop 7
	ds_write_b32 v8, v240 offset:4288
	ds_write_b32 v8, v241 offset:4544
	ds_write_b32 v8, v242 offset:4800
	ds_write_b32 v8, v243 offset:5056
	v_mov_b32_e32 v10, 0
	v_mov_b32_e32 v11, 0
	v_lshrrev_b32_e32 v17, 6, v194
	v_cmp_lt_u32_e32 vcc, v14, v17
	v_lshl_add_u32 v0, v14, 2, v15
	v_lshl_add_u32 v2, v17, 2, v15
	s_waitcnt lgkmcnt(0)
	s_barrier
	ds_read2st64_b32 v[0:1], v0 offset1:1
	ds_read_b32 v7, v18 offset:55296
	ds_read_b32 v2, v2
	v_mov_b32_e32 v6, 0
	s_waitcnt lgkmcnt(0)
	v_sub_f32_e32 v2, v2, v0
	v_min_f32_e32 v2, 0, v2
	v_mul_f32_e32 v2, 0x3fb8aa3b, v2
	v_exp_f32_e32 v8, v2
	v_or_b32_e32 v2, 64, v17
	v_lshl_add_u32 v3, v2, 2, v15
	ds_read_b32 v3, v3
	s_waitcnt lgkmcnt(0)
	v_sub_f32_e32 v3, v3, v1
	v_min_f32_e32 v3, 0, v3
	v_mul_f32_e32 v3, 0x3fb8aa3b, v3
	v_exp_f32_e32 v9, v3
	s_and_saveexec_b64 s[0:1], vcc
	s_cbranch_execz .LBB0_295
	v_lshl_add_u32 v5, v2, 2, v13
	v_lshl_add_u32 v3, v17, 2, v13
	ds_read_b32 v2, v18 offset:38912
	ds_read_b32 v4, v3
	ds_read_b32 v5, v5
	s_waitcnt lgkmcnt(0)
	v_pk_mul_f32 v[2:3], v[2:3], v[4:5] op_sel_hi:[0,1]
	v_pk_mul_f32 v[10:11], v[8:9], v[2:3]
